# attention: a wave whose 32 query rows all precede a key tile (tile fully masked for it) skips that tile's QK/softmax/PV (exactly-zero contribution), keeps loads / LDS writes / barrier
# speedup vs baseline: 1.0085x; 1.0037x over previous
.LBB0_1482:
	s_cmp_gt_i32 s52, s49
	s_cbranch_scc1 .LBB0_1481
	s_add_i32 s54, s47, 31
	s_cmp_gt_i32 s52, s54
	s_cbranch_scc1 .LBB0_1481

.LaF1_fast:
	s_add_i32 s54, s47, 31
	s_cmp_gt_i32 s52, s54
	s_cbranch_scc1 .LaF1_skip
	s_waitcnt vmcnt(0)
	s_bitcmp1_b32 s51, 0
	s_cselect_b32 s53, 0, 0xac00
	s_setprio 1
	v_add_u32_e32 v253, s53, v171
	v_add_u32_e32 v252, s53, v181
	ds_read_b128 v[196:199], v253
	ds_read_b128 v[200:203], v253 offset:12800
	ds_read_b128 v[204:207], v253 offset:32
	ds_read_b128 v[208:211], v253 offset:12832
	ds_read_b128 v[212:215], v253 offset:64
	ds_read_b128 v[216:219], v253 offset:12864
	s_waitcnt lgkmcnt(5)
	v_mfma_f32_32x32x16_bf16 v[66:81], v[196:199], v[110:113], 0
	ds_read_b128 v[220:223], v253 offset:96
	v_lshl_add_u64 v[244:245], s[2:3], 0, v[176:177]
	s_waitcnt lgkmcnt(5)
	v_mfma_f32_32x32x16_bf16 v[82:97], v[200:203], v[110:113], 0
	ds_read_b128 v[224:227], v253 offset:12896
	v_add_co_u32_e32 v246, vcc, 0x16020000, v244
	s_waitcnt lgkmcnt(5)
	v_mfma_f32_32x32x16_bf16 v[66:81], v[204:207], v[118:121], v[66:81]
	ds_read_b128 v[228:231], v253 offset:128
	s_nop 1
	s_waitcnt lgkmcnt(5)
	v_mfma_f32_32x32x16_bf16 v[82:97], v[208:211], v[118:121], v[82:97]
	ds_read_b128 v[232:235], v253 offset:12928
	v_addc_co_u32_e32 v247, vcc, 0, v245, vcc
	s_waitcnt lgkmcnt(5)
	v_mfma_f32_32x32x16_bf16 v[66:81], v[212:215], v[122:125], v[66:81]
	ds_read_b128 v[236:239], v253 offset:160
	v_add_co_u32_e32 v244, vcc, 0x16030000, v244
	s_waitcnt lgkmcnt(5)
	v_mfma_f32_32x32x16_bf16 v[82:97], v[216:219], v[122:125], v[82:97]
	ds_read_b128 v[240:243], v253 offset:12960
	s_nop 1
	s_waitcnt lgkmcnt(5)
	v_mfma_f32_32x32x16_bf16 v[66:81], v[220:223], v[126:129], v[66:81]
	ds_read_b128 v[196:199], v253 offset:192
	v_addc_co_u32_e32 v245, vcc, 0, v245, vcc
	s_waitcnt lgkmcnt(5)
	v_mfma_f32_32x32x16_bf16 v[82:97], v[224:227], v[126:129], v[82:97]
	ds_read_b128 v[200:203], v253 offset:12992
	global_load_dwordx4 v[98:101], v[246:247], off
	s_waitcnt lgkmcnt(5)
	v_mfma_f32_32x32x16_bf16 v[66:81], v[228:231], v[130:133], v[66:81]
	ds_read_b128 v[204:207], v253 offset:224
	global_load_dwordx4 v[102:105], v[244:245], off
	s_waitcnt lgkmcnt(5)
	v_mfma_f32_32x32x16_bf16 v[82:97], v[232:235], v[130:133], v[82:97]
	ds_read_b128 v[208:211], v253 offset:13024
	v_lshl_add_u64 v[246:247], s[2:3], 0, v[178:179]
	s_waitcnt lgkmcnt(5)
	v_mfma_f32_32x32x16_bf16 v[66:81], v[236:239], v[134:137], v[66:81]
	ds_read_b128 v[212:215], v253 offset:256
	v_add_co_u32_e32 v248, vcc, 0x1a000000, v246
	s_waitcnt lgkmcnt(5)
	v_mfma_f32_32x32x16_bf16 v[82:97], v[240:243], v[134:137], v[82:97]
	ds_read_b128 v[216:219], v253 offset:13056
	v_lshl_add_u64 v[244:245], s[2:3], 0, v[174:175]
	s_waitcnt lgkmcnt(5)
	v_mfma_f32_32x32x16_bf16 v[66:81], v[196:199], v[138:141], v[66:81]
	ds_read_b128 v[220:223], v253 offset:288
	s_nop 0
	s_waitcnt lgkmcnt(5)
	v_mfma_f32_32x32x16_bf16 v[82:97], v[200:203], v[138:141], v[82:97]
	ds_read_b128 v[224:227], v253 offset:13088
	v_addc_co_u32_e32 v249, vcc, 0, v247, vcc
	s_waitcnt lgkmcnt(5)
	v_mfma_f32_32x32x16_bf16 v[66:81], v[204:207], v[142:145], v[66:81]
	ds_read_b128 v[228:231], v253 offset:320
	global_load_dwordx4 v[106:109], v[244:245], off
	s_waitcnt lgkmcnt(5)
	v_mfma_f32_32x32x16_bf16 v[82:97], v[208:211], v[142:145], v[82:97]
	ds_read_b128 v[232:235], v253 offset:13120
	global_load_dwordx4 v[114:117], v[248:249], off offset:128
	s_waitcnt lgkmcnt(5)
	v_mfma_f32_32x32x16_bf16 v[66:81], v[212:215], v[150:153], v[66:81]
	ds_read_b128 v[236:239], v253 offset:352
	v_add_co_u32_e32 v244, vcc, 0x1a400000, v246
	s_waitcnt lgkmcnt(5)
	v_mfma_f32_32x32x16_bf16 v[82:97], v[216:219], v[150:153], v[82:97]
	ds_read_b128 v[240:243], v253 offset:13152
	s_nop 1
	s_waitcnt lgkmcnt(5)
	v_mfma_f32_32x32x16_bf16 v[66:81], v[220:223], v[154:157], v[66:81]
	v_addc_co_u32_e32 v245, vcc, 0, v247, vcc
	s_waitcnt lgkmcnt(4)
	v_mfma_f32_32x32x16_bf16 v[82:97], v[224:227], v[154:157], v[82:97]
	global_load_dwordx4 v[146:149], v[244:245], off offset:128
	s_waitcnt lgkmcnt(3)
	v_mfma_f32_32x32x16_bf16 v[66:81], v[228:231], v[158:161], v[66:81]
	s_waitcnt lgkmcnt(2)
	v_mfma_f32_32x32x16_bf16 v[82:97], v[232:235], v[158:161], v[82:97]
	s_waitcnt lgkmcnt(1)
	v_mfma_f32_32x32x16_bf16 v[66:81], v[236:239], v[162:165], v[66:81]
	s_waitcnt lgkmcnt(0)
	v_mfma_f32_32x32x16_bf16 v[82:97], v[240:243], v[162:165], v[82:97]
	ds_read_b128 v[196:199], v252 offset:25600
	ds_read_b128 v[200:203], v252 offset:30208
	ds_read_b128 v[204:207], v252 offset:34816
	ds_read_b128 v[208:211], v252 offset:39424
	ds_read_b128 v[212:215], v252 offset:25632
	ds_read_b128 v[216:219], v252 offset:30240
	s_setprio 0
	s_add_i32 s54, s52, 63
	s_cmp_le_i32 s54, s47
	s_cbranch_scc1 .LaF1_1
	v_add_u32_e32 v0, s52, v168
	v_add_u32_e32 v184, 32, v0
	v_cmp_le_i32_e32 vcc, v184, v173
	v_add_u32_e32 v184, 33, v0
	s_nop 3
	v_cndmask_b32_e32 v82, v180, v82, vcc
	v_cmp_lt_i32_e32 vcc, v0, v173
	s_nop 1
	v_cndmask_b32_e32 v67, v180, v67, vcc
	v_cmp_le_i32_e32 vcc, v0, v173
	s_nop 1
	v_cndmask_b32_e32 v66, v180, v66, vcc
	v_cmp_le_i32_e32 vcc, v184, v173
	v_add_u32_e32 v184, 2, v0
	s_nop 0
	v_cndmask_b32_e32 v83, v180, v83, vcc
	v_cmp_le_i32_e32 vcc, v184, v173
	v_add_u32_e32 v184, 34, v0
	s_nop 0
	v_cndmask_b32_e32 v68, v180, v68, vcc
	v_cmp_le_i32_e32 vcc, v184, v173
	v_add_u32_e32 v184, 3, v0
	s_nop 0
	v_cndmask_b32_e32 v84, v180, v84, vcc
	v_cmp_le_i32_e32 vcc, v184, v173
	v_add_u32_e32 v184, 35, v0
	s_nop 0
	v_cndmask_b32_e32 v69, v180, v69, vcc
	v_cmp_le_i32_e32 vcc, v184, v173
	v_add_u32_e32 v184, 4, v0
	s_nop 0
	v_cndmask_b32_e32 v85, v180, v85, vcc
	v_cmp_le_i32_e32 vcc, v184, v173
	v_add_u32_e32 v184, 36, v0
	s_nop 0
	v_cndmask_b32_e32 v70, v180, v70, vcc
	v_cmp_le_i32_e32 vcc, v184, v173
	v_add_u32_e32 v184, 5, v0
	s_nop 0
	v_cndmask_b32_e32 v86, v180, v86, vcc
	v_cmp_le_i32_e32 vcc, v184, v173
	v_add_u32_e32 v184, 37, v0
	s_nop 0
	v_cndmask_b32_e32 v71, v180, v71, vcc
	v_cmp_le_i32_e32 vcc, v184, v173
	v_add_u32_e32 v184, 6, v0
	s_nop 0
	v_cndmask_b32_e32 v87, v180, v87, vcc
	v_cmp_le_i32_e32 vcc, v184, v173
	v_add_u32_e32 v184, 38, v0
	s_nop 0
	v_cndmask_b32_e32 v72, v180, v72, vcc
	v_cmp_le_i32_e32 vcc, v184, v173
	v_add_u32_e32 v184, 7, v0
	s_nop 0
	v_cndmask_b32_e32 v88, v180, v88, vcc
	v_cmp_le_i32_e32 vcc, v184, v173
	v_add_u32_e32 v184, 39, v0
	s_nop 0
	v_cndmask_b32_e32 v73, v180, v73, vcc
	v_cmp_le_i32_e32 vcc, v184, v173
	v_add_u32_e32 v184, 16, v0
	s_nop 0
	v_cndmask_b32_e32 v89, v180, v89, vcc
	v_cmp_le_i32_e32 vcc, v184, v173
	v_add_u32_e32 v184, 48, v0
	s_nop 0
	v_cndmask_b32_e32 v74, v180, v74, vcc
	v_cmp_le_i32_e32 vcc, v184, v173
	v_add_u32_e32 v184, 17, v0
	s_nop 0
	v_cndmask_b32_e32 v90, v180, v90, vcc
	v_cmp_le_i32_e32 vcc, v184, v173
	v_add_u32_e32 v184, 49, v0
	s_nop 0
	v_cndmask_b32_e32 v75, v180, v75, vcc
	v_cmp_le_i32_e32 vcc, v184, v173
	v_add_u32_e32 v184, 18, v0
	s_nop 0
	v_cndmask_b32_e32 v91, v180, v91, vcc
	v_cmp_le_i32_e32 vcc, v184, v173
	v_add_u32_e32 v184, 50, v0
	s_nop 0
	v_cndmask_b32_e32 v76, v180, v76, vcc
	v_cmp_le_i32_e32 vcc, v184, v173
	v_add_u32_e32 v184, 19, v0
	s_nop 0
	v_cndmask_b32_e32 v92, v180, v92, vcc
	v_cmp_le_i32_e32 vcc, v184, v173
	v_add_u32_e32 v184, 51, v0
	s_nop 0
	v_cndmask_b32_e32 v77, v180, v77, vcc
	v_cmp_le_i32_e32 vcc, v184, v173
	v_add_u32_e32 v184, 20, v0
	s_nop 0
	v_cndmask_b32_e32 v93, v180, v93, vcc
	v_cmp_le_i32_e32 vcc, v184, v173
	v_add_u32_e32 v184, 52, v0
	s_nop 0
	v_cndmask_b32_e32 v78, v180, v78, vcc
	v_cmp_le_i32_e32 vcc, v184, v173
	v_add_u32_e32 v184, 21, v0
	s_nop 0
	v_cndmask_b32_e32 v94, v180, v94, vcc
	v_cmp_le_i32_e32 vcc, v184, v173
	v_add_u32_e32 v184, 53, v0
	s_nop 0
	v_cndmask_b32_e32 v79, v180, v79, vcc
	v_cmp_le_i32_e32 vcc, v184, v173
	v_add_u32_e32 v184, 22, v0
	s_nop 0
	v_cndmask_b32_e32 v95, v180, v95, vcc
	v_cmp_le_i32_e32 vcc, v184, v173
	v_add_u32_e32 v184, 54, v0
	s_nop 0
	v_cndmask_b32_e32 v80, v180, v80, vcc
	v_cmp_le_i32_e32 vcc, v184, v173
	v_add_u32_e32 v184, 23, v0
	v_add_u32_e32 v0, 55, v0
	v_cndmask_b32_e32 v96, v180, v96, vcc
	v_cmp_le_i32_e32 vcc, v184, v173
	s_nop 1
	v_cndmask_b32_e32 v81, v180, v81, vcc
	v_cmp_le_i32_e32 vcc, v0, v173
	s_nop 1
	v_cndmask_b32_e32 v97, v180, v97, vcc

.LaF1_skip:
	v_lshl_add_u64 v[66:67], s[2:3], 0, v[176:177]
	v_add_co_u32_e32 v68, vcc, 0x16020000, v66
	s_nop 1
	v_addc_co_u32_e32 v69, vcc, 0, v67, vcc
	v_add_co_u32_e32 v66, vcc, 0x16030000, v66
	s_nop 1
	v_addc_co_u32_e32 v67, vcc, 0, v67, vcc
	global_load_dwordx4 v[98:101], v[68:69], off
	global_load_dwordx4 v[102:105], v[66:67], off
	v_lshl_add_u64 v[68:69], s[2:3], 0, v[178:179]
	v_add_co_u32_e32 v70, vcc, 0x1a000000, v68
	v_lshl_add_u64 v[66:67], s[2:3], 0, v[174:175]
	s_nop 0
	v_addc_co_u32_e32 v71, vcc, 0, v69, vcc
	global_load_dwordx4 v[106:109], v[66:67], off
	global_load_dwordx4 v[114:117], v[70:71], off offset:128
	v_add_co_u32_e32 v66, vcc, 0x1a400000, v68
	s_nop 1
	v_addc_co_u32_e32 v67, vcc, 0, v69, vcc
	global_load_dwordx4 v[146:149], v[66:67], off offset:128
	s_branch .LBB0_1488

.LBB0_1494:
	s_cmp_gt_i32 s37, s47
	s_cbranch_scc1 .LBB0_1493
	s_add_i32 s26, s30, 31
	s_cmp_gt_i32 s37, s26
	s_cbranch_scc1 .LBB0_1493

.LaF2_fast:
	s_add_i32 s26, s30, 31
	s_cmp_gt_i32 s37, s26
	s_cbranch_scc1 .LaF2_skip
	s_waitcnt vmcnt(0)
	s_bitcmp1_b32 s36, 0
	s_cselect_b32 s4, 0, 0xac00
	s_setprio 1
	v_add_u32_e32 v253, s4, v171
	v_add_u32_e32 v252, s4, v181
	ds_read_b128 v[196:199], v253
	ds_read_b128 v[200:203], v253 offset:12800
	ds_read_b128 v[204:207], v253 offset:32
	ds_read_b128 v[208:211], v253 offset:12832
	ds_read_b128 v[212:215], v253 offset:64
	ds_read_b128 v[216:219], v253 offset:12864
	s_waitcnt lgkmcnt(5)
	v_mfma_f32_32x32x16_bf16 v[66:81], v[196:199], v[110:113], 0
	ds_read_b128 v[220:223], v253 offset:96
	v_lshl_add_u64 v[244:245], s[2:3], 0, v[176:177]
	s_waitcnt lgkmcnt(5)
	v_mfma_f32_32x32x16_bf16 v[82:97], v[200:203], v[110:113], 0
	ds_read_b128 v[224:227], v253 offset:12896
	v_add_co_u32_e32 v246, vcc, 0x16020000, v244
	s_waitcnt lgkmcnt(5)
	v_mfma_f32_32x32x16_bf16 v[66:81], v[204:207], v[114:117], v[66:81]
	ds_read_b128 v[228:231], v253 offset:128
	s_nop 1
	s_waitcnt lgkmcnt(5)
	v_mfma_f32_32x32x16_bf16 v[82:97], v[208:211], v[114:117], v[82:97]
	ds_read_b128 v[232:235], v253 offset:12928
	v_addc_co_u32_e32 v247, vcc, 0, v245, vcc
	s_waitcnt lgkmcnt(5)
	v_mfma_f32_32x32x16_bf16 v[66:81], v[212:215], v[118:121], v[66:81]
	ds_read_b128 v[236:239], v253 offset:160
	v_add_co_u32_e32 v244, vcc, 0x16030000, v244
	s_waitcnt lgkmcnt(5)
	v_mfma_f32_32x32x16_bf16 v[82:97], v[216:219], v[118:121], v[82:97]
	ds_read_b128 v[240:243], v253 offset:12960
	s_nop 1
	s_waitcnt lgkmcnt(5)
	v_mfma_f32_32x32x16_bf16 v[66:81], v[220:223], v[122:125], v[66:81]
	ds_read_b128 v[196:199], v253 offset:192
	v_addc_co_u32_e32 v245, vcc, 0, v245, vcc
	s_waitcnt lgkmcnt(5)
	v_mfma_f32_32x32x16_bf16 v[82:97], v[224:227], v[122:125], v[82:97]
	ds_read_b128 v[200:203], v253 offset:12992
	global_load_dwordx4 v[98:101], v[246:247], off
	s_waitcnt lgkmcnt(5)
	v_mfma_f32_32x32x16_bf16 v[66:81], v[228:231], v[130:133], v[66:81]
	ds_read_b128 v[204:207], v253 offset:224
	global_load_dwordx4 v[102:105], v[244:245], off
	s_waitcnt lgkmcnt(5)
	v_mfma_f32_32x32x16_bf16 v[82:97], v[232:235], v[130:133], v[82:97]
	ds_read_b128 v[208:211], v253 offset:13024
	v_lshl_add_u64 v[246:247], s[2:3], 0, v[178:179]
	s_waitcnt lgkmcnt(5)
	v_mfma_f32_32x32x16_bf16 v[66:81], v[236:239], v[134:137], v[66:81]
	ds_read_b128 v[212:215], v253 offset:256
	v_add_co_u32_e32 v248, vcc, 0x1a000000, v246
	s_waitcnt lgkmcnt(5)
	v_mfma_f32_32x32x16_bf16 v[82:97], v[240:243], v[134:137], v[82:97]
	ds_read_b128 v[216:219], v253 offset:13056
	v_lshl_add_u64 v[244:245], s[2:3], 0, v[174:175]
	s_waitcnt lgkmcnt(5)
	v_mfma_f32_32x32x16_bf16 v[66:81], v[196:199], v[138:141], v[66:81]
	ds_read_b128 v[220:223], v253 offset:288
	s_nop 0
	s_waitcnt lgkmcnt(5)
	v_mfma_f32_32x32x16_bf16 v[82:97], v[200:203], v[138:141], v[82:97]
	ds_read_b128 v[224:227], v253 offset:13088
	v_addc_co_u32_e32 v249, vcc, 0, v247, vcc
	s_waitcnt lgkmcnt(5)
	v_mfma_f32_32x32x16_bf16 v[66:81], v[204:207], v[142:145], v[66:81]
	ds_read_b128 v[228:231], v253 offset:320
	global_load_dwordx4 v[106:109], v[244:245], off
	s_waitcnt lgkmcnt(5)
	v_mfma_f32_32x32x16_bf16 v[82:97], v[208:211], v[142:145], v[82:97]
	ds_read_b128 v[232:235], v253 offset:13120
	global_load_dwordx4 v[126:129], v[248:249], off offset:128
	s_waitcnt lgkmcnt(5)
	v_mfma_f32_32x32x16_bf16 v[66:81], v[212:215], v[146:149], v[66:81]
	ds_read_b128 v[236:239], v253 offset:352
	v_add_co_u32_e32 v244, vcc, 0x1a400000, v246
	s_waitcnt lgkmcnt(5)
	v_mfma_f32_32x32x16_bf16 v[82:97], v[216:219], v[146:149], v[82:97]
	ds_read_b128 v[240:243], v253 offset:13152
	s_nop 1
	s_waitcnt lgkmcnt(5)
	v_mfma_f32_32x32x16_bf16 v[66:81], v[220:223], v[154:157], v[66:81]
	v_addc_co_u32_e32 v245, vcc, 0, v247, vcc
	s_waitcnt lgkmcnt(4)
	v_mfma_f32_32x32x16_bf16 v[82:97], v[224:227], v[154:157], v[82:97]
	global_load_dwordx4 v[150:153], v[244:245], off offset:128
	s_waitcnt lgkmcnt(3)
	v_mfma_f32_32x32x16_bf16 v[66:81], v[228:231], v[158:161], v[66:81]
	s_waitcnt lgkmcnt(2)
	v_mfma_f32_32x32x16_bf16 v[82:97], v[232:235], v[158:161], v[82:97]
	s_waitcnt lgkmcnt(1)
	v_mfma_f32_32x32x16_bf16 v[66:81], v[236:239], v[162:165], v[66:81]
	s_waitcnt lgkmcnt(0)
	v_mfma_f32_32x32x16_bf16 v[82:97], v[240:243], v[162:165], v[82:97]
	ds_read_b128 v[196:199], v252 offset:25600
	ds_read_b128 v[200:203], v252 offset:30208
	ds_read_b128 v[204:207], v252 offset:34816
	ds_read_b128 v[208:211], v252 offset:39424
	ds_read_b128 v[212:215], v252 offset:25632
	ds_read_b128 v[216:219], v252 offset:30240
	s_setprio 0
	s_add_i32 s26, s37, 63
	s_cmp_le_i32 s26, s30
	s_cbranch_scc1 .LaF2_1
	v_add_u32_e32 v0, s37, v168
	v_add_u32_e32 v184, 32, v0
	v_cmp_le_i32_e32 vcc, v184, v173
	v_add_u32_e32 v184, 33, v0
	s_nop 3
	v_cndmask_b32_e32 v82, v180, v82, vcc
	v_cmp_lt_i32_e32 vcc, v0, v173
	s_nop 1
	v_cndmask_b32_e32 v67, v180, v67, vcc
	v_cmp_le_i32_e32 vcc, v0, v173
	s_nop 1
	v_cndmask_b32_e32 v66, v180, v66, vcc
	v_cmp_le_i32_e32 vcc, v184, v173
	v_add_u32_e32 v184, 2, v0
	s_nop 0
	v_cndmask_b32_e32 v83, v180, v83, vcc
	v_cmp_le_i32_e32 vcc, v184, v173
	v_add_u32_e32 v184, 34, v0
	s_nop 0
	v_cndmask_b32_e32 v68, v180, v68, vcc
	v_cmp_le_i32_e32 vcc, v184, v173
	v_add_u32_e32 v184, 3, v0
	s_nop 0
	v_cndmask_b32_e32 v84, v180, v84, vcc
	v_cmp_le_i32_e32 vcc, v184, v173
	v_add_u32_e32 v184, 35, v0
	s_nop 0
	v_cndmask_b32_e32 v69, v180, v69, vcc
	v_cmp_le_i32_e32 vcc, v184, v173
	v_add_u32_e32 v184, 4, v0
	s_nop 0
	v_cndmask_b32_e32 v85, v180, v85, vcc
	v_cmp_le_i32_e32 vcc, v184, v173
	v_add_u32_e32 v184, 36, v0
	s_nop 0
	v_cndmask_b32_e32 v70, v180, v70, vcc
	v_cmp_le_i32_e32 vcc, v184, v173
	v_add_u32_e32 v184, 5, v0
	s_nop 0
	v_cndmask_b32_e32 v86, v180, v86, vcc
	v_cmp_le_i32_e32 vcc, v184, v173
	v_add_u32_e32 v184, 37, v0
	s_nop 0
	v_cndmask_b32_e32 v71, v180, v71, vcc
	v_cmp_le_i32_e32 vcc, v184, v173
	v_add_u32_e32 v184, 6, v0
	s_nop 0
	v_cndmask_b32_e32 v87, v180, v87, vcc
	v_cmp_le_i32_e32 vcc, v184, v173
	v_add_u32_e32 v184, 38, v0
	s_nop 0
	v_cndmask_b32_e32 v72, v180, v72, vcc
	v_cmp_le_i32_e32 vcc, v184, v173
	v_add_u32_e32 v184, 7, v0
	s_nop 0
	v_cndmask_b32_e32 v88, v180, v88, vcc
	v_cmp_le_i32_e32 vcc, v184, v173
	v_add_u32_e32 v184, 39, v0
	s_nop 0
	v_cndmask_b32_e32 v73, v180, v73, vcc
	v_cmp_le_i32_e32 vcc, v184, v173
	v_add_u32_e32 v184, 16, v0
	s_nop 0
	v_cndmask_b32_e32 v89, v180, v89, vcc
	v_cmp_le_i32_e32 vcc, v184, v173
	v_add_u32_e32 v184, 48, v0
	s_nop 0
	v_cndmask_b32_e32 v74, v180, v74, vcc
	v_cmp_le_i32_e32 vcc, v184, v173
	v_add_u32_e32 v184, 17, v0
	s_nop 0
	v_cndmask_b32_e32 v90, v180, v90, vcc
	v_cmp_le_i32_e32 vcc, v184, v173
	v_add_u32_e32 v184, 49, v0
	s_nop 0
	v_cndmask_b32_e32 v75, v180, v75, vcc
	v_cmp_le_i32_e32 vcc, v184, v173
	v_add_u32_e32 v184, 18, v0
	s_nop 0
	v_cndmask_b32_e32 v91, v180, v91, vcc
	v_cmp_le_i32_e32 vcc, v184, v173
	v_add_u32_e32 v184, 50, v0
	s_nop 0
	v_cndmask_b32_e32 v76, v180, v76, vcc
	v_cmp_le_i32_e32 vcc, v184, v173
	v_add_u32_e32 v184, 19, v0
	s_nop 0
	v_cndmask_b32_e32 v92, v180, v92, vcc
	v_cmp_le_i32_e32 vcc, v184, v173
	v_add_u32_e32 v184, 51, v0
	s_nop 0
	v_cndmask_b32_e32 v77, v180, v77, vcc
	v_cmp_le_i32_e32 vcc, v184, v173
	v_add_u32_e32 v184, 20, v0
	s_nop 0
	v_cndmask_b32_e32 v93, v180, v93, vcc
	v_cmp_le_i32_e32 vcc, v184, v173
	v_add_u32_e32 v184, 52, v0
	s_nop 0
	v_cndmask_b32_e32 v78, v180, v78, vcc
	v_cmp_le_i32_e32 vcc, v184, v173
	v_add_u32_e32 v184, 21, v0
	s_nop 0
	v_cndmask_b32_e32 v94, v180, v94, vcc
	v_cmp_le_i32_e32 vcc, v184, v173
	v_add_u32_e32 v184, 53, v0
	s_nop 0
	v_cndmask_b32_e32 v79, v180, v79, vcc
	v_cmp_le_i32_e32 vcc, v184, v173
	v_add_u32_e32 v184, 22, v0
	s_nop 0
	v_cndmask_b32_e32 v95, v180, v95, vcc
	v_cmp_le_i32_e32 vcc, v184, v173
	v_add_u32_e32 v184, 54, v0
	s_nop 0
	v_cndmask_b32_e32 v80, v180, v80, vcc
	v_cmp_le_i32_e32 vcc, v184, v173
	v_add_u32_e32 v184, 23, v0
	v_add_u32_e32 v0, 55, v0
	v_cndmask_b32_e32 v96, v180, v96, vcc
	v_cmp_le_i32_e32 vcc, v184, v173
	s_nop 1
	v_cndmask_b32_e32 v81, v180, v81, vcc
	v_cmp_le_i32_e32 vcc, v0, v173
	s_nop 1
	v_cndmask_b32_e32 v97, v180, v97, vcc

.LaF2_skip:
	v_lshl_add_u64 v[66:67], s[2:3], 0, v[176:177]
	v_add_co_u32_e32 v68, vcc, 0x16020000, v66
	s_nop 1
	v_addc_co_u32_e32 v69, vcc, 0, v67, vcc
	v_add_co_u32_e32 v66, vcc, 0x16030000, v66
	s_nop 1
	v_addc_co_u32_e32 v67, vcc, 0, v67, vcc
	global_load_dwordx4 v[98:101], v[68:69], off
	global_load_dwordx4 v[102:105], v[66:67], off
	v_lshl_add_u64 v[68:69], s[2:3], 0, v[178:179]
	v_add_co_u32_e32 v70, vcc, 0x1a000000, v68
	v_lshl_add_u64 v[66:67], s[2:3], 0, v[174:175]
	s_nop 0
	v_addc_co_u32_e32 v71, vcc, 0, v69, vcc
	global_load_dwordx4 v[106:109], v[66:67], off
	global_load_dwordx4 v[126:129], v[70:71], off offset:128
	v_add_co_u32_e32 v66, vcc, 0x1a400000, v68
	s_nop 1
	v_addc_co_u32_e32 v67, vcc, 0, v69, vcc
	global_load_dwordx4 v[150:153], v[66:67], off offset:128
	s_branch .LBB0_1500
